# v51 with waves 0-3 kept at s_setprio 1 for the whole kernel (no resets at phase ends)
# speedup vs baseline: 1.0097x; 1.0097x over previous
_Z8mega_fwd4Args:
	s_load_dword s85, s[0:1], 0xd8
	s_load_dwordx4 s[56:59], s[0:1], 0xc0
	s_load_dwordx2 s[90:91], s[0:1], 0xd0
	s_add_u32 s4, s0, 0xd0
	v_and_b32_e32 v220, 0x3ff, v0
	s_mov_b32 s88, s2
	s_addc_u32 s5, s1, 0
	v_readfirstlane_b32 s78, v220
	s_nop 3
	s_cmp_lt_u32 s78, 0x100
	s_cbranch_scc0 .Lprio_init_done
	s_setprio 1
.Lprio_init_done:
	v_cmp_gt_u32_e32 vcc, 4, v220
	s_and_saveexec_b64 s[2:3], vcc
	v_lshl_add_u32 v1, v220, 2, 0
	v_add_u32_e32 v1, 0x23fc0, v1
	v_mov_b32_e32 v2, 0
	ds_write_b32 v1, v2
	s_or_b64 exec, exec, s[2:3]
	s_waitcnt lgkmcnt(0)
	s_sub_i32 s2, s59, s58
	s_cmp_lt_i32 s2, 2
	s_barrier
	s_cbranch_scc1 .LBB0_24
	s_cmp_lg_u32 s88, 0
	s_cbranch_scc1 .LBB0_13
	s_add_u32 s6, s56, 0x21280000
	v_lshlrev_b32_e32 v2, 2, v220
	s_addc_u32 s7, s57, 0
	v_lshrrev_b32_e32 v1, 9, v220
	v_mov_b32_e32 v3, 0
	v_add_u32_e32 v4, 0x800, v2
	v_xor_b32_e32 v1, 7, v1
	global_store_dword v2, v3, s[6:7]
	global_store_dword v4, v3, s[6:7]
	v_or_b32_e32 v4, 0x1000, v2
	v_add_u32_e32 v2, 0x1800, v2
	global_store_dword v4, v3, s[6:7]
	global_store_dword v2, v3, s[6:7]
	v_add_u32_e32 v2, 0xa00, v220
	v_or_b32_e32 v4, 0x800, v220
	v_cmp_lt_u32_e32 vcc, 4, v1
	v_cmp_lt_u32_e64 s[2:3], 3, v1
	s_and_saveexec_b64 s[8:9], s[2:3]
	s_cbranch_execz .LBB0_6
	v_lshlrev_b32_e32 v4, 2, v4
	global_store_dword v4, v3, s[6:7]
